# gMLP gated-output stores non-temporal
# baseline (speedup 1.0000x reference)
; #define LAS __attribute__((address_space(3)))
; __device__ __forceinline__ float bflo(unsigned u) { return __uint_as_float(u << 16); }
; __device__ __forceinline__ float bfhi(unsigned u) { return __uint_as_float(u & 0xffff0000u); }
; __device__ __forceinline__ unsigned short f2bf(float f) { return (unsigned short)(pk2(f, 0.f) & 0xffffu); }
; __device__ __forceinline__ void gmlp_unit(LAS unsigned char* lds, int unit, const bf16* U, const bf16* Vb, bf16* Y, const float* vs1, const float* vs2,
;                                           const float* lnw, const float* lnb, const float* bs) {
;     ...
;     const size_t m0 = (size_t)bn * 128; const int c0 = g * 128;
;     const int t = 16 * w + l16;
;     v4u uu[4], gg[4];
; #pragma unroll
;     for (int j = 0; j < 4; ++j) { const size_t off = (m0 + t) * 1024 + c0 + 32 * j + 8 * g4; uu[j] = *(const v4u*)(U + off); gg[j] = *(const v4u*)(Y + off); }
;     {
;         const int s = tid >> 2, cq = (tid & 3) * 32;
;         const size_t row = m0 + s;
;         const float mean = vs1[row] * (1.f / 1024.f); const float var = vs2[row] * (1.f / 1024.f) - mean * mean; const float rstd = rsqrtf(fmaxf(var, 0.f) + EPS);
; #pragma unroll
;         for (int j = 0; j < 4; ++j) {
;             const int cc = cq + 8 * j;
;             const v4u vr = *(const v4u*)(Vb + row * 1024 + c0 + cc);
;             const f32x4 w0 = *(const f32x4*)(lnw + c0 + cc), w1 = *(const f32x4*)(lnw + c0 + cc + 4), b0 = *(const f32x4*)(lnb + c0 + cc), b1 = *(const f32x4*)(lnb + c0 + cc + 4);
;             LAS bf16* vd = Vt + cc * 136 + s;
;             vd[0 * 136] = f2bf((bflo(vr.x) - mean) * rstd * w0[0] + b0[0]); vd[1 * 136] = f2bf((bfhi(vr.x) - mean) * rstd * w0[1] + b0[1]);
;             vd[2 * 136] = f2bf((bflo(vr.y) - mean) * rstd * w0[2] + b0[2]); vd[3 * 136] = f2bf((bfhi(vr.y) - mean) * rstd * w0[3] + b0[3]);
;             vd[4 * 136] = f2bf((bflo(vr.z) - mean) * rstd * w1[0] + b1[0]); vd[5 * 136] = f2bf((bfhi(vr.z) - mean) * rstd * w1[1] + b1[1]);
;             vd[6 * 136] = f2bf((bflo(vr.w) - mean) * rstd * w1[2] + b1[2]); vd[7 * 136] = f2bf((bfhi(vr.w) - mean) * rstd * w1[3] + b1[3]);
;         }
.Lg3_nf:
	s_add_u32 s4, s42, s2
	s_addc_u32 s5, s43, s3
	s_add_u32 s2, s44, s2
	s_addc_u32 s3, s45, s3
	global_load_dwordx4 v[46:49], v89, s[4:5] offset:48
	global_load_dwordx4 v[58:61], v89, s[4:5] offset:32
	global_load_dwordx4 v[66:69], v89, s[4:5] offset:16
	global_load_dwordx4 v[74:77], v89, s[4:5]
	global_load_dwordx4 v[50:53], v89, s[2:3] offset:48
	global_load_dwordx4 v[62:65], v89, s[2:3] offset:32
	global_load_dwordx4 v[70:73], v89, s[2:3] offset:16
	global_load_dwordx4 v[78:81], v89, s[2:3]
	global_load_dwordx4 v[200:203], v89, s[4:5] offset:112
	global_load_dwordx4 v[204:207], v89, s[4:5] offset:96
	global_load_dwordx4 v[208:211], v89, s[4:5] offset:80
	global_load_dwordx4 v[224:227], v89, s[4:5] offset:64
	global_load_dwordx4 v[212:215], v89, s[2:3] offset:112
	global_load_dwordx4 v[216:219], v89, s[2:3] offset:96
	global_load_dwordx4 v[220:223], v89, s[2:3] offset:80
	global_load_dwordx4 v[228:231], v89, s[2:3] offset:64
	v_add_u32_e32 v198, s26, v84
	v_ashrrev_i32_e32 v199, 31, v198
	v_lshl_add_u64 v[198:199], v[198:199], 2, s[48:49]
	global_load_dword v232, v[198:199], off
	s_waitcnt vmcnt(17)
	v_mov_b32_e32 v30, v92
	v_mov_b32_e32 v31, v93
	v_mov_b32_e32 v32, v94
	v_mov_b32_e32 v33, v95
	v_mov_b32_e32 v22, v96
	v_mov_b32_e32 v23, v97
	v_mov_b32_e32 v24, v98
	v_mov_b32_e32 v25, v99
	v_mov_b32_e32 v14, v100
	v_mov_b32_e32 v15, v101
	v_mov_b32_e32 v16, v102
	v_mov_b32_e32 v17, v103
	v_mov_b32_e32 v6, v104
	v_mov_b32_e32 v7, v105
	v_mov_b32_e32 v8, v106
	v_mov_b32_e32 v9, v107
	v_mov_b32_e32 v26, v108
	v_mov_b32_e32 v27, v109
	v_mov_b32_e32 v28, v110
	v_mov_b32_e32 v29, v111
	v_mov_b32_e32 v18, v112
	v_mov_b32_e32 v19, v113
	v_mov_b32_e32 v20, v114
	v_mov_b32_e32 v21, v115
	v_mov_b32_e32 v10, v116
	v_mov_b32_e32 v11, v117
	v_mov_b32_e32 v12, v118
	v_mov_b32_e32 v13, v119
	v_mov_b32_e32 v2, v120
	v_mov_b32_e32 v3, v121
	v_mov_b32_e32 v4, v122
	v_mov_b32_e32 v5, v123
	v_mov_b32_e32 v34, v124
	v_mov_b32_e32 v35, v125
	v_mov_b32_e32 v36, v126
	v_mov_b32_e32 v37, v127
	v_mov_b32_e32 v38, v128
	v_mov_b32_e32 v39, v129
	v_mov_b32_e32 v40, v130
	v_mov_b32_e32 v41, v131
	v_mov_b32_e32 v42, v132
	v_mov_b32_e32 v43, v133
	v_mov_b32_e32 v44, v134
	v_mov_b32_e32 v45, v135
	v_mov_b32_e32 v54, v246
	v_mov_b32_e32 v55, v247
	v_mov_b32_e32 v56, v248
	v_mov_b32_e32 v57, v249
	v_mov_b32_e32 v197, v244
	v_mov_b32_e32 v196, v245
	v_mul_u32_u24_e32 v90, 0x110, v90
	s_add_i32 s7, s7, s84
	s_lshl_b64 s[0:1], s[26:27], 1
	s_waitcnt vmcnt(0)
	v_mul_f32_e32 v86, 0x3a800000, v196
	v_mul_f32_e32 v87, 0x3a800000, v197
	v_fma_f32 v233, -v87, v87, v86
	v_max_f32_e32 v233, 0, v233
	v_add_f32_e32 v233, 0x358637bd, v233
	v_rsq_f32_e32 v85, v233
	s_nop 0
	v_add3_u32 v86, 0, v235, v90
	v_lshlrev_b32_e32 v90, 16, v54
	v_and_b32_e32 v54, 0xffff0000, v54
	v_sub_f32_e32 v54, v54, v87
	v_mul_f32_e32 v54, v54, v85
	v_fma_f32 v54, v75, v54, v79
	v_cvt_pk_bf16_f32 v54, v54, s0
	ds_write_b16 v86, v54 offset:35088
	v_lshlrev_b32_e32 v54, 16, v55
	v_sub_f32_e32 v54, v54, v87
	v_mul_f32_e32 v54, v54, v85
	v_fma_f32 v54, v76, v54, v80
	v_cvt_pk_bf16_f32 v54, v54, s0
	ds_write_b16 v86, v54 offset:35360
	v_and_b32_e32 v54, 0xffff0000, v55
	v_sub_f32_e32 v54, v54, v87
	v_mul_f32_e32 v54, v54, v85
	v_fmac_f32_e32 v81, v77, v54
	v_cvt_pk_bf16_f32 v54, v81, s0
	ds_write_b16 v86, v54 offset:35632
	v_lshlrev_b32_e32 v54, 16, v56
	v_sub_f32_e32 v54, v54, v87
	v_mul_f32_e32 v54, v54, v85
	v_fma_f32 v54, v66, v54, v70
	v_cvt_pk_bf16_f32 v54, v54, s0
	ds_write_b16 v86, v54 offset:35904
	v_and_b32_e32 v54, 0xffff0000, v56
	v_sub_f32_e32 v54, v54, v87
	v_mul_f32_e32 v54, v54, v85
	v_fma_f32 v54, v67, v54, v71
	v_cvt_pk_bf16_f32 v54, v54, s0
	ds_write_b16 v86, v54 offset:36176
	v_lshlrev_b32_e32 v54, 16, v57
	v_sub_f32_e32 v54, v54, v87
	v_mul_f32_e32 v54, v54, v85
	v_fma_f32 v54, v68, v54, v72
	v_cvt_pk_bf16_f32 v54, v54, s0
	ds_write_b16 v86, v54 offset:36448
	v_and_b32_e32 v54, 0xffff0000, v57
	v_sub_f32_e32 v54, v54, v87
	v_mul_f32_e32 v54, v54, v85
	v_fmac_f32_e32 v73, v69, v54
	v_cvt_pk_bf16_f32 v54, v73, s0
	ds_write_b16 v86, v54 offset:36720
	v_lshlrev_b32_e32 v54, 16, v42
	v_and_b32_e32 v42, 0xffff0000, v42
	v_sub_f32_e32 v42, v42, v87
	v_mul_f32_e32 v42, v85, v42
	v_fma_f32 v42, v59, v42, v63
	v_cvt_pk_bf16_f32 v42, v42, s0
	ds_write_b16 v86, v42 offset:37264
	v_lshlrev_b32_e32 v42, 16, v43
	v_sub_f32_e32 v42, v42, v87
	v_mul_f32_e32 v42, v85, v42
	v_fma_f32 v42, v60, v42, v64
	v_cvt_pk_bf16_f32 v42, v42, s0
	ds_write_b16 v86, v42 offset:37536
	v_and_b32_e32 v42, 0xffff0000, v43
	v_sub_f32_e32 v42, v42, v87
	v_mul_f32_e32 v42, v85, v42
	v_fmac_f32_e32 v65, v61, v42
	v_cvt_pk_bf16_f32 v42, v65, s0
	ds_write_b16 v86, v42 offset:37808
	v_lshlrev_b32_e32 v42, 16, v44
	v_sub_f32_e32 v42, v42, v87
	v_mul_f32_e32 v42, v85, v42
	v_fma_f32 v42, v46, v42, v50
	v_cvt_pk_bf16_f32 v42, v42, s0
	ds_write_b16 v86, v42 offset:38080
	v_and_b32_e32 v42, 0xffff0000, v44
	v_sub_f32_e32 v42, v42, v87
	v_mul_f32_e32 v42, v85, v42
	v_fma_f32 v42, v47, v42, v51
	v_cvt_pk_bf16_f32 v42, v42, s0
	ds_write_b16 v86, v42 offset:38352
	v_lshlrev_b32_e32 v42, 16, v45
	v_sub_f32_e32 v42, v42, v87
	v_mul_f32_e32 v42, v85, v42
	v_fma_f32 v42, v48, v42, v52
	v_cvt_pk_bf16_f32 v42, v42, s0
	ds_write_b16 v86, v42 offset:38624
	v_and_b32_e32 v42, 0xffff0000, v45
	v_sub_f32_e32 v90, v90, v87
	v_sub_f32_e32 v54, v54, v87
	v_sub_f32_e32 v42, v42, v87
	v_mul_f32_e32 v90, v90, v85
	v_mul_f32_e32 v54, v85, v54
	v_mul_f32_e32 v42, v85, v42
	v_fma_f32 v74, v74, v90, v78
	v_fma_f32 v54, v58, v54, v62
	v_fmac_f32_e32 v53, v49, v42
	v_cvt_pk_bf16_f32 v74, v74, s0
	v_cvt_pk_bf16_f32 v54, v54, s0
	v_cvt_pk_bf16_f32 v42, v53, s0
; #define LAS __attribute__((address_space(3)))
; __device__ __forceinline__ float bflo(unsigned u) { return __uint_as_float(u << 16); }
; __device__ __forceinline__ float bfhi(unsigned u) { return __uint_as_float(u & 0xffff0000u); }
; __device__ __forceinline__ unsigned short f2bf(float f) { return (unsigned short)(pk2(f, 0.f) & 0xffffu); }
; #define LBAR() do { asm volatile("s_waitcnt lgkmcnt(0)" ::: "memory"); __builtin_amdgcn_s_barrier(); asm volatile("" ::: "memory"); } while (0)
; __device__ __forceinline__ void gmlp_unit(LAS unsigned char* lds, int unit, const bf16* U, const bf16* Vb, bf16* Y, const float* vs1, const float* vs2,
;                                           const float* lnw, const float* lnb, const float* bs) {
;     ...
;     const size_t m0 = (size_t)bn * 128; const int c0 = g * 128;
;     const int t = 16 * w + l16;
;     v4u uu[4], gg[4];
; #pragma unroll
;     for (int j = 0; j < 4; ++j) { const size_t off = (m0 + t) * 1024 + c0 + 32 * j + 8 * g4; uu[j] = *(const v4u*)(U + off); gg[j] = *(const v4u*)(Y + off); }
;     {
;         const int s = tid >> 2, cq = (tid & 3) * 32;
;         const size_t row = m0 + s;
;         const float mean = vs1[row] * (1.f / 1024.f); const float var = vs2[row] * (1.f / 1024.f) - mean * mean; const float rstd = rsqrtf(fmaxf(var, 0.f) + EPS);
; #pragma unroll
;         for (int j = 0; j < 4; ++j) {
;             const int cc = cq + 8 * j;
;             const v4u vr = *(const v4u*)(Vb + row * 1024 + c0 + cc);
;             const f32x4 w0 = *(const f32x4*)(lnw + c0 + cc), w1 = *(const f32x4*)(lnw + c0 + cc + 4), b0 = *(const f32x4*)(lnb + c0 + cc), b1 = *(const f32x4*)(lnb + c0 + cc + 4);
;             LAS bf16* vd = Vt + cc * 136 + s;
;             vd[0 * 136] = f2bf((bflo(vr.x) - mean) * rstd * w0[0] + b0[0]); vd[1 * 136] = f2bf((bfhi(vr.x) - mean) * rstd * w0[1] + b0[1]);
;             vd[2 * 136] = f2bf((bflo(vr.y) - mean) * rstd * w0[2] + b0[2]); vd[3 * 136] = f2bf((bfhi(vr.y) - mean) * rstd * w0[3] + b0[3]);
;             vd[4 * 136] = f2bf((bflo(vr.z) - mean) * rstd * w1[0] + b1[0]); vd[5 * 136] = f2bf((bfhi(vr.z) - mean) * rstd * w1[1] + b1[1]);
;             vd[6 * 136] = f2bf((bflo(vr.w) - mean) * rstd * w1[2] + b1[2]); vd[7 * 136] = f2bf((bfhi(vr.w) - mean) * rstd * w1[3] + b1[3]);
;         }
;     }
;     LBAR();
	ds_write_b16 v86, v74 offset:34816
	ds_write_b16 v86, v54 offset:36992
	ds_write_b16 v86, v42 offset:38896
	v_lshlrev_b32_e32 v74, 16, v38
	v_and_b32_e32 v38, 0xffff0000, v38
	v_sub_f32_e32 v38, v38, v87
	v_mul_f32_e32 v38, v85, v38
	v_sub_f32_e32 v74, v74, v87
	v_mul_f32_e32 v74, v85, v74
	s_movk_i32 s2, 0x110
	v_fma_f32 v38, v225, v38, v229
	v_cvt_pk_bf16_f32 v38, v38, s0
	ds_write_b16 v86, v38 offset:39440
	v_lshlrev_b32_e32 v38, 16, v39
	v_sub_f32_e32 v38, v38, v87
	v_mul_f32_e32 v38, v85, v38
	v_fma_f32 v38, v226, v38, v230
	v_cvt_pk_bf16_f32 v38, v38, s0
	ds_write_b16 v86, v38 offset:39712
	v_and_b32_e32 v38, 0xffff0000, v39
	v_sub_f32_e32 v38, v38, v87
	v_mul_f32_e32 v38, v85, v38
	v_fmac_f32_e32 v231, v227, v38
	v_cvt_pk_bf16_f32 v38, v231, s0
	ds_write_b16 v86, v38 offset:39984
	v_lshlrev_b32_e32 v38, 16, v40
	v_sub_f32_e32 v38, v38, v87
	v_mul_f32_e32 v38, v85, v38
	v_fma_f32 v38, v208, v38, v220
	v_cvt_pk_bf16_f32 v38, v38, s0
	ds_write_b16 v86, v38 offset:40256
	v_and_b32_e32 v38, 0xffff0000, v40
	v_sub_f32_e32 v38, v38, v87
	v_mul_f32_e32 v38, v85, v38
	v_fma_f32 v38, v209, v38, v221
	v_cvt_pk_bf16_f32 v38, v38, s0
	ds_write_b16 v86, v38 offset:40528
	v_lshlrev_b32_e32 v38, 16, v41
	v_sub_f32_e32 v38, v38, v87
	v_mul_f32_e32 v38, v85, v38
	v_fma_f32 v38, v210, v38, v222
	v_cvt_pk_bf16_f32 v38, v38, s0
	ds_write_b16 v86, v38 offset:40800
	v_and_b32_e32 v38, 0xffff0000, v41
	v_sub_f32_e32 v38, v38, v87
	v_mul_f32_e32 v38, v85, v38
	v_fmac_f32_e32 v223, v211, v38
	v_cvt_pk_bf16_f32 v38, v223, s0
	ds_write_b16 v86, v38 offset:41072
	v_lshlrev_b32_e32 v38, 16, v34
	v_and_b32_e32 v34, 0xffff0000, v34
	v_sub_f32_e32 v34, v34, v87
	v_mul_f32_e32 v34, v85, v34
	v_fma_f32 v34, v205, v34, v217
	v_cvt_pk_bf16_f32 v34, v34, s0
	ds_write_b16 v86, v34 offset:41616
	v_lshlrev_b32_e32 v34, 16, v35
	v_sub_f32_e32 v34, v34, v87
	v_mul_f32_e32 v34, v85, v34
	v_fma_f32 v34, v206, v34, v218
	v_cvt_pk_bf16_f32 v34, v34, s0
	ds_write_b16 v86, v34 offset:41888
	v_and_b32_e32 v34, 0xffff0000, v35
	v_sub_f32_e32 v34, v34, v87
	v_mul_f32_e32 v34, v85, v34
	v_fmac_f32_e32 v219, v207, v34
	v_cvt_pk_bf16_f32 v34, v219, s0
	ds_write_b16 v86, v34 offset:42160
	v_lshlrev_b32_e32 v34, 16, v36
	v_sub_f32_e32 v34, v34, v87
	v_mul_f32_e32 v34, v85, v34
	v_fma_f32 v34, v200, v34, v212
	v_cvt_pk_bf16_f32 v34, v34, s0
	ds_write_b16 v86, v34 offset:42432
	v_and_b32_e32 v34, 0xffff0000, v36
	v_sub_f32_e32 v34, v34, v87
	v_mul_f32_e32 v34, v85, v34
	v_fma_f32 v34, v201, v34, v213
	v_cvt_pk_bf16_f32 v34, v34, s0
	ds_write_b16 v86, v34 offset:42704
	v_lshlrev_b32_e32 v34, 16, v37
	v_sub_f32_e32 v34, v34, v87
	v_mul_f32_e32 v34, v85, v34
	v_fma_f32 v34, v202, v34, v214
	v_cvt_pk_bf16_f32 v34, v34, s0
	ds_write_b16 v86, v34 offset:42976
	v_and_b32_e32 v34, 0xffff0000, v37
	v_sub_f32_e32 v38, v38, v87
	v_sub_f32_e32 v34, v34, v87
	v_mul_f32_e32 v38, v85, v38
	v_mul_f32_e32 v34, v85, v34
	v_fma_f32 v224, v224, v74, v228
	v_fma_f32 v38, v204, v38, v216
	v_fmac_f32_e32 v215, v203, v34
	v_cvt_pk_bf16_f32 v224, v224, s0
	v_cvt_pk_bf16_f32 v38, v38, s0
	v_cvt_pk_bf16_f32 v34, v215, s0
	v_add_u32_e32 v50, s26, v84
	ds_write_b16 v86, v224 offset:39168
	ds_write_b16 v86, v38 offset:41344
	ds_write_b16 v86, v34 offset:43248
	s_sub_i32 s100, s7, s84
	s_cmpk_lt_i32 s7, 0x400
	s_cselect_b32 s100, s7, s100
	s_ashr_i32 s4, s100, 3
	s_ashr_i32 s5, s4, 31
	s_lshl_b64 s[4:5], s[4:5], 7
	s_and_b32 s100, s100, 7
	s_lshl_b32 s100, s100, 7
	v_mov_b32_e32 v36, v84
	v_mov_b32_e32 v37, 0
	v_lshl_add_u64 v[36:37], s[4:5], 0, v[36:37]
	v_lshlrev_b64 v[36:37], 10, v[36:37]
	v_or_b32_e32 v36, s100, v36
	v_or_b32_e32 v37, s27, v37
	v_lshl_or_b32 v36, v88, 3, v36
	v_lshlrev_b64 v[36:37], 1, v[36:37]
	v_lshl_add_u64 v[38:39], s[34:35], 0, v[36:37]
	v_lshl_add_u64 v[40:41], s[50:51], 0, v[36:37]
	global_load_dwordx4 v[92:95], v[38:39], off
	global_load_dwordx4 v[96:99], v[38:39], off offset:64
	global_load_dwordx4 v[100:103], v[38:39], off offset:128
	global_load_dwordx4 v[104:107], v[38:39], off offset:192
	global_load_dwordx4 v[108:111], v[40:41], off
	global_load_dwordx4 v[112:115], v[40:41], off offset:64
	global_load_dwordx4 v[116:119], v[40:41], off offset:128
	global_load_dwordx4 v[120:123], v[40:41], off offset:192
	v_ashrrev_i32_e32 v42, 2, v145
	v_ashrrev_i32_e32 v43, 31, v42
	v_lshl_add_u64 v[42:43], s[4:5], 0, v[42:43]
	v_lshlrev_b64 v[44:45], 2, v[42:43]
	v_readlane_b32 s4, v251, 21
	v_readlane_b32 s5, v251, 22
	s_nop 1
	v_lshl_add_u64 v[46:47], s[4:5], 0, v[44:45]
	global_load_dword v244, v[46:47], off
	v_readlane_b32 s4, v251, 23
	v_readlane_b32 s5, v251, 24
	s_nop 1
	v_lshl_add_u64 v[46:47], s[4:5], 0, v[44:45]
	global_load_dword v245, v[46:47], off
	v_lshlrev_b64 v[42:43], 11, v[42:43]
	v_readlane_b32 s4, v253, 0
	v_readlane_b32 s5, v253, 1
	s_nop 1
	v_lshl_add_u64 v[42:43], s[4:5], 0, v[42:43]
	s_lshl_b32 s4, s100, 1
	s_mov_b32 s5, 0
	v_lshl_add_u64 v[42:43], v[42:43], 0, s[4:5]
	v_and_b32_e32 v48, 3, v145
	v_lshlrev_b32_e32 v48, 6, v48
	v_mov_b32_e32 v49, 0
	v_lshl_add_u64 v[42:43], v[42:43], 0, v[48:49]
	global_load_dwordx4 v[124:127], v[42:43], off offset:48
	global_load_dwordx4 v[128:131], v[42:43], off offset:32
	global_load_dwordx4 v[132:135], v[42:43], off offset:16
	global_load_dwordx4 v[246:249], v[42:43], off
	v_mul_lo_u32 v34, v84, s2
	v_lshlrev_b32_e32 v54, 4, v88
	v_ashrrev_i32_e32 v51, 31, v50
	s_waitcnt lgkmcnt(0)
	s_barrier
; #define LAS __attribute__((address_space(3)))
; __device__ __forceinline__ float bflo(unsigned u) { return __uint_as_float(u << 16); }
; __device__ __forceinline__ float bfhi(unsigned u) { return __uint_as_float(u & 0xffff0000u); }
; __device__ __forceinline__ unsigned pk2(float lo, float hi) { f32x2_t v = {lo, hi}; bf16x2_t b = __builtin_convertvector(v, bf16x2_t); return __builtin_bit_cast(unsigned, b); }
; __device__ __forceinline__ f32x4 mfma16(bf16x8 a, bf16x8 b, f32x4 c) { return __builtin_amdgcn_mfma_f32_16x16x32_bf16(a, b, c, 0, 0, 0); }
; __device__ __forceinline__ void gmlp_unit(LAS unsigned char* lds, int unit, const bf16* U, const bf16* Vb, bf16* Y, const float* vs1, const float* vs2,
;                                           const float* lnw, const float* lnb, const float* bs) {
;     ...
;     bf16x8 bw[4];
; #pragma unroll
;     for (int ks = 0; ks < 4; ++ks) bw[ks] = *(const LAS bf16x8*)(Wa + (16 * w + l16) * 136 + 32 * ks + 8 * g4);
;     const float bias = bs[g * 128 + t];
; #pragma unroll
;     for (int j = 0; j < 4; ++j) {
;         const int crow = 32 * j + 8 * (l16 >> 2) + (l16 & 3);
;         f32x4 e4 = (f32x4){0.f, 0.f, 0.f, 0.f}, o4 = e4;
; #pragma unroll
;         for (int ks = 0; ks < 4; ++ks) {
;             const bf16x8 ae = *(const LAS bf16x8*)(Vt + crow * 136 + 32 * ks + 8 * g4), ao = *(const LAS bf16x8*)(Vt + (crow + 4) * 136 + 32 * ks + 8 * g4);
;             e4 = mfma16(ae, bw[ks], e4); o4 = mfma16(ao, bw[ks], o4);
;         }
;         const size_t off = (m0 + t) * 1024 + c0 + 32 * j + 8 * g4;
;         const v4u u4 = uu[j], g4v = gg[j];
;         v4u y;
;         y.x = pk2(bflo(u4.x) * (e4[0] + bias) * bflo(g4v.x), bfhi(u4.x) * (e4[1] + bias) * bfhi(g4v.x)); y.y = pk2(bflo(u4.y) * (e4[2] + bias) * bflo(g4v.y), bfhi(u4.y) * (e4[3] + bias) * bfhi(g4v.y));
;         y.z = pk2(bflo(u4.z) * (o4[0] + bias) * bflo(g4v.z), bfhi(u4.z) * (o4[1] + bias) * bfhi(g4v.z)); y.w = pk2(bflo(u4.w) * (o4[2] + bias) * bflo(g4v.w), bfhi(u4.w) * (o4[3] + bias) * bfhi(g4v.w));
;         *(v4u*)(Y + off) = y;
	v_add3_u32 v34, 0, v34, v54
	v_lshl_add_u64 v[50:51], v[50:51], 2, s[48:49]
	ds_read_b128 v[46:49], v34
	ds_read_b128 v[42:45], v34 offset:64
	ds_read_b128 v[38:41], v34 offset:128
	ds_read_b128 v[34:37], v34 offset:192
	v_mov_b32_e32 v50, v232
	v_lshlrev_b32_e32 v51, 1, v1
	v_and_b32_e32 v1, 3, v1
	v_and_or_b32 v1, v51, 24, v1
	v_lshlrev_b64 v[52:53], 11, v[82:83]
	v_lshl_add_u64 v[52:53], s[50:51], 0, v[52:53]
	v_mul_u32_u24_e32 v1, 0x110, v1
	v_lshl_add_u64 v[52:53], v[52:53], 0, s[0:1]
	v_mov_b32_e32 v55, v0
	v_add3_u32 v1, 0, v1, v54
	v_lshl_add_u64 v[52:53], v[52:53], 0, v[54:55]
	ds_read_b128 v[54:57], v1 offset:34816
	ds_read_b128 v[58:61], v1 offset:35904
	ds_read_b128 v[62:65], v1 offset:34880
	ds_read_b128 v[66:69], v1 offset:35968
	s_waitcnt lgkmcnt(3)
	v_mfma_f32_16x16x32_bf16 v[54:57], v[54:57], v[46:49], 0
	v_readlane_b32 s0, v254, 54
	s_add_i32 s6, s6, s0
	s_cmpk_gt_i32 s7, 0x3ff
	s_waitcnt lgkmcnt(2)
	v_mfma_f32_16x16x32_bf16 v[58:61], v[58:61], v[46:49], 0
	s_waitcnt lgkmcnt(1)
	v_mfma_f32_16x16x32_bf16 v[54:57], v[62:65], v[42:45], v[54:57]
	s_waitcnt lgkmcnt(0)
	v_mfma_f32_16x16x32_bf16 v[58:61], v[66:69], v[42:45], v[58:61]
	ds_read_b128 v[62:65], v1 offset:34944
	ds_read_b128 v[66:69], v1 offset:36032
	s_waitcnt lgkmcnt(1)
	v_mfma_f32_16x16x32_bf16 v[54:57], v[62:65], v[38:41], v[54:57]
	s_waitcnt lgkmcnt(0)
	v_mfma_f32_16x16x32_bf16 v[58:61], v[66:69], v[38:41], v[58:61]
	ds_read_b128 v[62:65], v1 offset:35008
	ds_read_b128 v[66:69], v1 offset:36096
	s_waitcnt lgkmcnt(1)
	v_mfma_f32_16x16x32_bf16 v[54:57], v[62:65], v[34:37], v[54:57]
	v_lshlrev_b32_e32 v62, 16, v30
	v_and_b32_e32 v63, 0xffff0000, v30
	v_lshlrev_b32_e32 v30, 16, v31
	s_waitcnt lgkmcnt(0)
	v_mfma_f32_16x16x32_bf16 v[58:61], v[66:69], v[34:37], v[58:61]
	v_and_b32_e32 v31, 0xffff0000, v31
	s_nop 0
	v_pk_add_f32 v[54:55], v[50:51], v[54:55] op_sel_hi:[0,1]
	v_pk_mul_f32 v[54:55], v[54:55], v[62:63]
	v_lshlrev_b32_e32 v62, 16, v26
	v_and_b32_e32 v63, 0xffff0000, v26
	v_pk_mul_f32 v[54:55], v[54:55], v[62:63]
	s_nop 0
	v_cvt_pk_bf16_f32 v26, v54, v55
	v_pk_add_f32 v[54:55], v[50:51], v[56:57] op_sel_hi:[0,1]
	v_pk_mul_f32 v[30:31], v[54:55], v[30:31]
	v_lshlrev_b32_e32 v54, 16, v27
	v_and_b32_e32 v55, 0xffff0000, v27
	v_pk_mul_f32 v[30:31], v[30:31], v[54:55]
	v_pk_add_f32 v[54:55], v[50:51], v[58:59] op_sel_hi:[0,1]
	v_cvt_pk_bf16_f32 v27, v30, v31
	v_lshlrev_b32_e32 v30, 16, v32
	v_and_b32_e32 v31, 0xffff0000, v32
	v_pk_mul_f32 v[30:31], v[54:55], v[30:31]
	v_lshlrev_b32_e32 v54, 16, v28
	v_and_b32_e32 v55, 0xffff0000, v28
	v_pk_mul_f32 v[30:31], v[30:31], v[54:55]
	s_nop 0
	v_cvt_pk_bf16_f32 v28, v30, v31
	v_lshlrev_b32_e32 v30, 16, v33
	v_and_b32_e32 v31, 0xffff0000, v33
	v_pk_add_f32 v[32:33], v[50:51], v[60:61] op_sel_hi:[0,1]
	v_pk_mul_f32 v[30:31], v[32:33], v[30:31]
	v_lshlrev_b32_e32 v32, 16, v29
	v_and_b32_e32 v33, 0xffff0000, v29
	v_pk_mul_f32 v[30:31], v[30:31], v[32:33]
	s_nop 0
	v_cvt_pk_bf16_f32 v29, v30, v31
	global_store_dwordx4 v[52:53], v[26:29], off nt
	ds_read_b128 v[26:29], v1 offset:43520
	ds_read_b128 v[30:33], v1 offset:44608
	ds_read_b128 v[54:57], v1 offset:43584
	ds_read_b128 v[58:61], v1 offset:44672
	s_waitcnt lgkmcnt(3)
	v_mfma_f32_16x16x32_bf16 v[26:29], v[26:29], v[46:49], 0
	s_waitcnt lgkmcnt(2)
	v_mfma_f32_16x16x32_bf16 v[30:33], v[30:33], v[46:49], 0
	s_waitcnt lgkmcnt(1)
	v_mfma_f32_16x16x32_bf16 v[26:29], v[54:57], v[42:45], v[26:29]
	s_waitcnt lgkmcnt(0)
	v_mfma_f32_16x16x32_bf16 v[30:33], v[58:61], v[42:45], v[30:33]
	ds_read_b128 v[54:57], v1 offset:43648
	ds_read_b128 v[58:61], v1 offset:44736
	s_waitcnt lgkmcnt(1)
	v_mfma_f32_16x16x32_bf16 v[26:29], v[54:57], v[38:41], v[26:29]
	s_waitcnt lgkmcnt(0)
	v_mfma_f32_16x16x32_bf16 v[30:33], v[58:61], v[38:41], v[30:33]
	ds_read_b128 v[54:57], v1 offset:43712
	ds_read_b128 v[58:61], v1 offset:44800
	s_waitcnt lgkmcnt(1)
	v_mfma_f32_16x16x32_bf16 v[26:29], v[54:57], v[34:37], v[26:29]
	v_lshlrev_b32_e32 v54, 16, v22
	v_and_b32_e32 v55, 0xffff0000, v22
	v_lshlrev_b32_e32 v22, 16, v23
	s_waitcnt lgkmcnt(0)
	v_mfma_f32_16x16x32_bf16 v[30:33], v[58:61], v[34:37], v[30:33]
	s_nop 2
	v_add_f32_e64 v26, v50, v26
	v_add_f32_e64 v27, v50, v27
	v_pk_mul_f32 v[26:27], v[26:27], v[54:55]
	v_lshlrev_b32_e32 v54, 16, v18
	v_and_b32_e32 v55, 0xffff0000, v18
	v_pk_mul_f32 v[26:27], v[26:27], v[54:55]
	v_and_b32_e32 v23, 0xffff0000, v23
	v_cvt_pk_bf16_f32 v18, v26, v27
	v_pk_add_f32 v[26:27], v[50:51], v[28:29] op_sel_hi:[0,1]
	v_pk_mul_f32 v[22:23], v[26:27], v[22:23]
	v_lshlrev_b32_e32 v26, 16, v19
	v_and_b32_e32 v27, 0xffff0000, v19
	v_pk_mul_f32 v[22:23], v[22:23], v[26:27]
	v_pk_add_f32 v[26:27], v[50:51], v[30:31] op_sel_hi:[0,1]
	v_cvt_pk_bf16_f32 v19, v22, v23
	v_lshlrev_b32_e32 v22, 16, v24
	v_and_b32_e32 v23, 0xffff0000, v24
	v_pk_mul_f32 v[22:23], v[26:27], v[22:23]
	v_lshlrev_b32_e32 v26, 16, v20
	v_and_b32_e32 v27, 0xffff0000, v20
	v_pk_mul_f32 v[22:23], v[22:23], v[26:27]
	s_nop 0
	v_cvt_pk_bf16_f32 v20, v22, v23
	v_lshlrev_b32_e32 v22, 16, v25
	v_and_b32_e32 v23, 0xffff0000, v25
	v_pk_add_f32 v[24:25], v[50:51], v[32:33] op_sel_hi:[0,1]
	v_pk_mul_f32 v[22:23], v[24:25], v[22:23]
	v_lshlrev_b32_e32 v24, 16, v21
	v_and_b32_e32 v25, 0xffff0000, v21
	v_pk_mul_f32 v[22:23], v[22:23], v[24:25]
	s_nop 0
	v_cvt_pk_bf16_f32 v21, v22, v23
	global_store_dwordx4 v[52:53], v[18:21], off offset:64 nt
	ds_read_b128 v[18:21], v1 offset:52224
	ds_read_b128 v[22:25], v1 offset:53312
	ds_read_b128 v[26:29], v1 offset:52288
	ds_read_b128 v[30:33], v1 offset:53376
	s_waitcnt lgkmcnt(3)
; #define LAS __attribute__((address_space(3)))
; __device__ __forceinline__ float bflo(unsigned u) { return __uint_as_float(u << 16); }
; __device__ __forceinline__ float bfhi(unsigned u) { return __uint_as_float(u & 0xffff0000u); }
; __device__ __forceinline__ unsigned pk2(float lo, float hi) { f32x2_t v = {lo, hi}; bf16x2_t b = __builtin_convertvector(v, bf16x2_t); return __builtin_bit_cast(unsigned, b); }
; __device__ __forceinline__ f32x4 mfma16(bf16x8 a, bf16x8 b, f32x4 c) { return __builtin_amdgcn_mfma_f32_16x16x32_bf16(a, b, c, 0, 0, 0); }
; #define LBAR() do { asm volatile("s_waitcnt lgkmcnt(0)" ::: "memory"); __builtin_amdgcn_s_barrier(); asm volatile("" ::: "memory"); } while (0)
; __device__ __forceinline__ void gmlp_unit(LAS unsigned char* lds, int unit, const bf16* U, const bf16* Vb, bf16* Y, const float* vs1, const float* vs2,
;                                           const float* lnw, const float* lnb, const float* bs) {
;     ...
;     for (int j = 0; j < 4; ++j) {
;         const int crow = 32 * j + 8 * (l16 >> 2) + (l16 & 3);
;         f32x4 e4 = (f32x4){0.f, 0.f, 0.f, 0.f}, o4 = e4;
; #pragma unroll
;         for (int ks = 0; ks < 4; ++ks) {
;             const bf16x8 ae = *(const LAS bf16x8*)(Vt + crow * 136 + 32 * ks + 8 * g4), ao = *(const LAS bf16x8*)(Vt + (crow + 4) * 136 + 32 * ks + 8 * g4);
;             e4 = mfma16(ae, bw[ks], e4); o4 = mfma16(ao, bw[ks], o4);
;         }
;         const size_t off = (m0 + t) * 1024 + c0 + 32 * j + 8 * g4;
;         const v4u u4 = uu[j], g4v = gg[j];
;         v4u y;
;         y.x = pk2(bflo(u4.x) * (e4[0] + bias) * bflo(g4v.x), bfhi(u4.x) * (e4[1] + bias) * bfhi(g4v.x)); y.y = pk2(bflo(u4.y) * (e4[2] + bias) * bflo(g4v.y), bfhi(u4.y) * (e4[3] + bias) * bfhi(g4v.y));
;         y.z = pk2(bflo(u4.z) * (o4[0] + bias) * bflo(g4v.z), bfhi(u4.z) * (o4[1] + bias) * bfhi(g4v.z)); y.w = pk2(bflo(u4.w) * (o4[2] + bias) * bflo(g4v.w), bfhi(u4.w) * (o4[3] + bias) * bfhi(g4v.w));
;         *(v4u*)(Y + off) = y;
;     }
;     LBAR();
	v_mfma_f32_16x16x32_bf16 v[18:21], v[18:21], v[46:49], 0
	s_waitcnt lgkmcnt(2)
	v_mfma_f32_16x16x32_bf16 v[22:25], v[22:25], v[46:49], 0
	s_waitcnt lgkmcnt(1)
	v_mfma_f32_16x16x32_bf16 v[18:21], v[26:29], v[42:45], v[18:21]
	s_waitcnt lgkmcnt(0)
	v_mfma_f32_16x16x32_bf16 v[22:25], v[30:33], v[42:45], v[22:25]
	ds_read_b128 v[26:29], v1 offset:52352
	ds_read_b128 v[30:33], v1 offset:53440
	s_waitcnt lgkmcnt(1)
	v_mfma_f32_16x16x32_bf16 v[18:21], v[26:29], v[38:41], v[18:21]
	s_waitcnt lgkmcnt(0)
	v_mfma_f32_16x16x32_bf16 v[22:25], v[30:33], v[38:41], v[22:25]
	ds_read_b128 v[26:29], v1 offset:52416
	ds_read_b128 v[30:33], v1 offset:53504
	s_waitcnt lgkmcnt(1)
	v_mfma_f32_16x16x32_bf16 v[18:21], v[26:29], v[34:37], v[18:21]
	v_lshlrev_b32_e32 v26, 16, v14
	v_and_b32_e32 v27, 0xffff0000, v14
	v_lshlrev_b32_e32 v14, 16, v15
	s_waitcnt lgkmcnt(0)
	v_mfma_f32_16x16x32_bf16 v[22:25], v[30:33], v[34:37], v[22:25]
	s_nop 2
	v_add_f32_e64 v18, v50, v18
	v_add_f32_e64 v19, v50, v19
	v_pk_mul_f32 v[18:19], v[18:19], v[26:27]
	v_lshlrev_b32_e32 v26, 16, v10
	v_and_b32_e32 v27, 0xffff0000, v10
	v_pk_mul_f32 v[18:19], v[18:19], v[26:27]
	v_and_b32_e32 v15, 0xffff0000, v15
	v_cvt_pk_bf16_f32 v10, v18, v19
	v_pk_add_f32 v[18:19], v[50:51], v[20:21] op_sel_hi:[0,1]
	v_pk_mul_f32 v[14:15], v[18:19], v[14:15]
	v_lshlrev_b32_e32 v18, 16, v11
	v_and_b32_e32 v19, 0xffff0000, v11
	v_pk_mul_f32 v[14:15], v[14:15], v[18:19]
	v_pk_add_f32 v[18:19], v[50:51], v[22:23] op_sel_hi:[0,1]
	v_cvt_pk_bf16_f32 v11, v14, v15
	v_lshlrev_b32_e32 v14, 16, v16
	v_and_b32_e32 v15, 0xffff0000, v16
	v_pk_mul_f32 v[14:15], v[18:19], v[14:15]
	v_lshlrev_b32_e32 v18, 16, v12
	v_and_b32_e32 v19, 0xffff0000, v12
	v_pk_mul_f32 v[14:15], v[14:15], v[18:19]
	s_nop 0
	v_cvt_pk_bf16_f32 v12, v14, v15
	v_lshlrev_b32_e32 v14, 16, v17
	v_and_b32_e32 v15, 0xffff0000, v17
	v_pk_add_f32 v[16:17], v[50:51], v[24:25] op_sel_hi:[0,1]
	v_pk_mul_f32 v[14:15], v[16:17], v[14:15]
	v_lshlrev_b32_e32 v16, 16, v13
	v_and_b32_e32 v17, 0xffff0000, v13
	v_pk_mul_f32 v[14:15], v[14:15], v[16:17]
	s_nop 0
	v_cvt_pk_bf16_f32 v13, v14, v15
	global_store_dwordx4 v[52:53], v[10:13], off offset:128 nt
	ds_read_b128 v[10:13], v1 offset:60928
	ds_read_b128 v[14:17], v1 offset:62016
	ds_read_b128 v[18:21], v1 offset:60992
	ds_read_b128 v[22:25], v1 offset:62080
	s_waitcnt lgkmcnt(3)
	v_mfma_f32_16x16x32_bf16 v[10:13], v[10:13], v[46:49], 0
	s_waitcnt lgkmcnt(2)
	v_mfma_f32_16x16x32_bf16 v[14:17], v[14:17], v[46:49], 0
	s_waitcnt lgkmcnt(1)
	v_mfma_f32_16x16x32_bf16 v[10:13], v[18:21], v[42:45], v[10:13]
	s_waitcnt lgkmcnt(0)
	v_mfma_f32_16x16x32_bf16 v[14:17], v[22:25], v[42:45], v[14:17]
	ds_read_b128 v[18:21], v1 offset:61056
	ds_read_b128 v[22:25], v1 offset:62144
	s_waitcnt lgkmcnt(1)
	v_mfma_f32_16x16x32_bf16 v[10:13], v[18:21], v[38:41], v[10:13]
	s_waitcnt lgkmcnt(0)
	v_mfma_f32_16x16x32_bf16 v[14:17], v[22:25], v[38:41], v[14:17]
	ds_read_b128 v[18:21], v1 offset:61120
	ds_read_b128 v[22:25], v1 offset:62208
	s_waitcnt lgkmcnt(1)
	v_mfma_f32_16x16x32_bf16 v[10:13], v[18:21], v[34:37], v[10:13]
	v_lshlrev_b32_e32 v18, 16, v6
	v_and_b32_e32 v19, 0xffff0000, v6
	v_lshlrev_b32_e32 v6, 16, v7
	s_waitcnt lgkmcnt(0)
	v_mfma_f32_16x16x32_bf16 v[14:17], v[22:25], v[34:37], v[14:17]
	s_nop 2
	v_add_f32_e64 v10, v50, v10
	v_add_f32_e64 v11, v50, v11
	v_pk_mul_f32 v[10:11], v[10:11], v[18:19]
	v_lshlrev_b32_e32 v18, 16, v2
	v_and_b32_e32 v19, 0xffff0000, v2
	v_pk_mul_f32 v[10:11], v[10:11], v[18:19]
	v_and_b32_e32 v7, 0xffff0000, v7
	v_cvt_pk_bf16_f32 v2, v10, v11
	v_pk_add_f32 v[10:11], v[50:51], v[12:13] op_sel_hi:[0,1]
	v_pk_mul_f32 v[6:7], v[10:11], v[6:7]
	v_lshlrev_b32_e32 v10, 16, v3
	v_and_b32_e32 v11, 0xffff0000, v3
	v_pk_mul_f32 v[6:7], v[6:7], v[10:11]
	v_pk_add_f32 v[10:11], v[50:51], v[14:15] op_sel_hi:[0,1]
	v_cvt_pk_bf16_f32 v3, v6, v7
	v_lshlrev_b32_e32 v6, 16, v8
	v_and_b32_e32 v7, 0xffff0000, v8
	v_pk_mul_f32 v[6:7], v[10:11], v[6:7]
	v_lshlrev_b32_e32 v10, 16, v4
	v_and_b32_e32 v11, 0xffff0000, v4
	v_pk_mul_f32 v[6:7], v[6:7], v[10:11]
	s_nop 0
	v_cvt_pk_bf16_f32 v4, v6, v7
	v_lshlrev_b32_e32 v6, 16, v9
	v_and_b32_e32 v7, 0xffff0000, v9
	v_pk_add_f32 v[8:9], v[50:51], v[16:17] op_sel_hi:[0,1]
	v_pk_mul_f32 v[6:7], v[8:9], v[6:7]
	v_lshlrev_b32_e32 v8, 16, v5
	v_and_b32_e32 v9, 0xffff0000, v5
	v_pk_mul_f32 v[6:7], v[6:7], v[8:9]
	s_nop 0
	v_cvt_pk_bf16_f32 v5, v6, v7
	global_store_dwordx4 v[52:53], v[2:5], off offset:192 nt
	s_waitcnt lgkmcnt(0)
	s_barrier
	s_cbranch_scc1 .LBB0_762
